# attention tile loop rewritten as two-barrier role-alternating pipeline (PV(t-1)+S(t) MFMA block vs softmax block, sub-1 offset by one barrier)
# speedup vs baseline: 1.0218x; 1.0218x over previous
; DI int opaque_tid() { int t = threadIdx.x; asm volatile("" : "+v"(t)); return t; }
; DI void attn_item(const Params& p, unsigned char* lds, int b, int hd, int qb, float lam) {
;     const int tid = opaque_tid(), lane = tid & 63, wave = tid >> 6, l31 = lane & 31, h = lane >> 5;
;     const int sub = wave >> 2, rt = wave & 3;
;     const bf16_t* aq = (const bf16_t*)((unsigned char*)p.out + DO_AQ);
;     const bf16_t* ak = (const bf16_t*)(p.ws + OFF_AK);
;     const bf16_t* avT = (const bf16_t*)(p.ws + OFF_AVT);
;     const bf16_t* akm = (const bf16_t*)(p.ws + OFF_AKM);
;     const bf16_t* avTm = (const bf16_t*)(p.ws + OFF_AVTM);
;     bf16_t* az = (bf16_t*)(p.ws + OFF_AZ);
;     const int qs = qb * 128 + rt * 32 + l31;
;     const size_t grow = (size_t)b * 4096 + qs;
;     bf16x8 qf[4];
; #pragma unroll
;     for (int ks = 0; ks < 4; ++ks) qf[ks] = *(const bf16x8*)(aq + grow * 1024 + hd * 128 + sub * 64 + ks * 16 + 8 * h);
;     f32x16 O[4];
; #pragma unroll
;     for (int d = 0; d < 4; ++d)
; #pragma unroll
;         for (int i = 0; i < 16; ++i) O[d][i] = 0.f;
;     float m = 0.f, l = 0.f;
;     const int T = 2 * qb + 3;
;     u32x4 k0r[2], v0r[2];
;     const int krow_ = tid >> 4, kc_ = tid & 15, vdv_ = tid >> 3, vc_ = tid & 7;
;     const bf16_t* kp = ak + ((size_t)b * 4096 + krow_) * 1024 + hd * 128 + kc_ * 8;
;     const bf16_t* vp_ = avT + ((size_t)(b * 8 + hd) * 128 + vdv_) * 4096 + vc_ * 8;
;     ...
;     {
;         const bf16_t* km_ = akm + (size_t)krow_ * 1024 + hd * 128 + kc_ * 8;
;         k0r[0] = *(const u32x4*)km_; k0r[1] = *(const u32x4*)(km_ + 32 * 1024);
;         const bf16_t* vm_ = avTm + (size_t)(hd * 128 + vdv_) * 64 + vc_ * 8;
;         v0r[0] = *(const u32x4*)vm_; v0r[1] = *(const u32x4*)(vm_ + 64 * 64);
;     }
;     u32x4 k1r[2], v1r[2];
;     A_LOAD_REAL(k1r, v1r);
; #pragma unroll
;     for (int ks = 0; ks < 4; ++ks) asm volatile("" : "+v"(qf[ks]));
;     A_STORE(k0r, v0r, 0);
;     __syncthreads();
.LBB0_1809:
	s_or_b64 exec, exec, s[4:5]
	s_add_i32 s0, 0, 0x25000
	s_cmp_lg_u32 s0, -1
	s_cselect_b32 s0, s0, 0
	s_cselect_b32 s4, s57, 0
	s_waitcnt vmcnt(0)
	v_mov_b32_e32 v2, s0
	v_mov_b32_e32 v3, s4
	s_waitcnt lgkmcnt(0)
	s_barrier
	flat_load_dword v1, v[2:3] sc0 sc1
	s_waitcnt vmcnt(0) lgkmcnt(0)
	s_barrier
	v_readfirstlane_b32 s8, v1
	s_cmp_eq_u32 s8, -1
	s_cbranch_scc1 .LBB0_1823
	s_lshr_b32 s9, s8, 16
	s_and_b32 s0, s8, 0xffff
	s_cmp_gt_u32 s0, 7
	s_mov_b64 s[4:5], -1
	s_cbranch_scc0 .LBB0_1831
	s_add_i32 s4, s0, -8
	s_lshr_b32 s0, s4, 2
	s_and_b32 s0, s0, 0x3ffffffc
	s_and_b32 s5, s8, 3
	s_or_b32 s0, s0, s5
	v_mov_b32_e32 v132, v186
	s_sub_i32 s0, 31, s0
	s_lshl_b32 s6, s0, 7
	v_lshrrev_b32_e32 v1, 1, v132
	v_and_b32_e32 v146, 31, v132
	v_and_b32_e32 v148, 0x60, v1
	s_bfe_u32 s11, s4, 0x20002
	v_or3_b32 v138, v148, s6, v146
	s_lshl_b32 s54, s11, 12
	v_ashrrev_i32_e32 v139, 31, v138
	v_lshl_add_u64 v[2:3], v[138:139], 0, s[54:55]
	v_ashrrev_i32_e32 v147, 8, v132
	v_lshlrev_b64 v[136:137], 11, v[2:3]
	v_lshl_add_u64 v[2:3], s[68:69], 0, v[136:137]
	s_lshl_b32 s6, s9, 8
	s_mov_b32 s7, s55
	v_lshlrev_b32_e32 v4, 6, v147
	v_lshl_add_u64 v[2:3], v[2:3], 0, s[6:7]
	v_ashrrev_i32_e32 v5, 31, v4
	v_lshl_add_u64 v[2:3], v[4:5], 1, v[2:3]
	v_ashrrev_i32_e32 v4, 4, v132
	v_ashrrev_i32_e32 v5, 31, v4
	v_lshlrev_b64 v[12:13], 11, v[4:5]
	v_bfe_u32 v149, v132, 5, 1
	v_lshlrev_b32_e32 v1, 4, v132
	v_lshl_add_u64 v[12:13], s[64:65], 0, v[12:13]
	v_lshlrev_b32_e32 v98, 4, v149
	v_and_b32_e32 v140, 0xf0, v1
	v_mov_b32_e32 v141, v99
	v_lshl_add_u64 v[12:13], v[12:13], 0, s[6:7]
	v_lshl_add_u64 v[2:3], v[2:3], 0, v[98:99]
	v_lshl_add_u64 v[12:13], v[12:13], 0, v[140:141]
	global_load_dwordx4 v[100:103], v[2:3], off
	global_load_dwordx4 v[104:107], v[2:3], off offset:32
	global_load_dwordx4 v[108:111], v[2:3], off offset:64
	global_load_dwordx4 v[112:115], v[2:3], off offset:96
	global_load_dwordx4 v[116:119], v[12:13], off
	v_add_co_u32_e32 v2, vcc, s43, v12
	s_lshl_b32 s10, s9, 7
	v_ashrrev_i32_e32 v6, 3, v132
	v_addc_co_u32_e32 v3, vcc, 0, v13, vcc
	global_load_dwordx4 v[120:123], v[2:3], off
	v_add_u32_e32 v2, s10, v6
	v_ashrrev_i32_e32 v3, 31, v2
	v_lshlrev_b64 v[2:3], 7, v[2:3]
	v_and_b32_e32 v10, 0x70, v1
	v_mov_b32_e32 v11, v99
	v_lshl_add_u64 v[2:3], s[62:63], 0, v[2:3]
	v_lshl_add_u64 v[2:3], v[2:3], 0, v[10:11]
	global_load_dwordx4 v[124:127], v[2:3], off
	v_lshl_add_u64 v[8:9], v[4:5], 0, s[54:55]
	v_lshlrev_b64 v[8:9], 11, v[8:9]
	v_add_co_u32_e32 v2, vcc, s56, v2
	v_lshl_add_u64 v[8:9], s[44:45], 0, v[8:9]
	s_lshl_b32 s11, s11, 10
	v_addc_co_u32_e32 v3, vcc, 0, v3, vcc
	v_lshl_add_u64 v[8:9], v[8:9], 0, s[6:7]
	s_add_i32 s54, s11, s10
	v_ashrrev_i32_e32 v7, 31, v6
	global_load_dwordx4 v[128:131], v[2:3], off
	v_lshl_add_u64 v[82:83], v[8:9], 0, v[140:141]
	v_lshl_add_u64 v[8:9], v[6:7], 0, s[54:55]
	v_lshlrev_b64 v[8:9], 13, v[8:9]
	v_lshl_add_u64 v[8:9], s[60:61], 0, v[8:9]
	v_add_co_u32_e32 v2, vcc, s43, v82
	v_lshl_add_u64 v[84:85], v[8:9], 0, v[10:11]
	s_nop 0
	v_addc_co_u32_e32 v3, vcc, 0, v83, vcc
	v_add_co_u32_e32 v8, vcc, s74, v84
	global_load_dwordx4 v[74:77], v[82:83], off
	global_load_dwordx4 v[70:73], v[84:85], off
	v_addc_co_u32_e32 v9, vcc, 0, v85, vcc
	global_load_dwordx4 v[78:81], v[2:3], off
	global_load_dwordx4 v[66:69], v[8:9], off
	v_lshlrev_b32_e32 v2, 3, v132
	v_mul_lo_u32 v139, v4, s75
	v_add_u32_e32 v4, 0x200, v132
	v_and_b32_e32 v150, 0x60, v1
	v_and_b32_e32 v151, 8, v2
	v_lshrrev_b32_e32 v5, 4, v4
	v_add3_u32 v1, 0, v150, v151
	v_mul_lo_u32 v152, v6, s52
	v_add_u32_e32 v3, 0, v140
	v_mul_lo_u32 v141, v5, s75
	v_add_u32_e32 v97, v1, v152
	v_add_u32_e32 v87, v3, v139
	v_add_u32_e32 v96, v3, v141
	v_add_u32_e32 v2, 0x4000, v97
	s_waitcnt vmcnt(11)
	s_waitcnt vmcnt(10)
	s_waitcnt vmcnt(9)
	s_waitcnt vmcnt(8)
	s_waitcnt vmcnt(7)
	ds_write_b128 v87, v[116:119]
	v_mad_u32_u24 v42, v146, s75, 0
	v_lshl_or_b32 v154, v147, 7, v98
	s_waitcnt vmcnt(6)
	ds_write_b128 v96, v[120:123]
	s_waitcnt vmcnt(5)
	ds_write2_b64 v2, v[124:125], v[126:127] offset0:128 offset1:130
	v_lshrrev_b32_e32 v2, 3, v4
	v_mul_lo_u32 v153, v2, s52
	v_add_u32_e32 v155, v1, v153
	v_add_u32_e32 v1, 0x4000, v155
	s_waitcnt vmcnt(4)
	ds_write2_b64 v1, v[128:129], v[130:131] offset0:128 offset1:130
	v_add_u32_e32 v1, v42, v154
	s_waitcnt lgkmcnt(0)
	s_barrier
; DI void attn_s(const unsigned char* sK, int tt, int qb, int qs, int sub, int l31, int h,
;                const bf16x8 (&qf)[4], f32x16 (&O)[4], float& m, float& l, bf16x8 (&pb)[4]) {
;     ...
;         for (int i = 0; i < 4; ++i) st[i & 1] = MFMA32(ka[i], qf[i >> 1], st[i & 1]);
;         __builtin_amdgcn_sched_barrier(0);
; #pragma unroll
;         for (int i = 0; i < 4; ++i) st[i & 1] = MFMA32(kc[i], qf[2 + (i >> 1)], st[i & 1]);
;     }
;     if (tt == 0) {
; #pragma unroll
;         for (int i = 0; i < 16; ++i) { st[0][i] = -INFINITY; if (i < 8) st[1][i] = -INFINITY; }
;     } else if (tt >= 2 * qb + 1) {
;         const int kbase = (tt - 1) * 64 + 4 * h;
; #pragma unroll
;         for (int k2 = 0; k2 < 2; ++k2)
; #pragma unroll
;             for (int i = 0; i < 16; ++i) {
;                 const int key = kbase + k2 * 32 + (i & 3) + 8 * (i >> 2);
;                 if (key > qs) st[k2][i] = -INFINITY;
;             }
;     }
;     float mx;
;     {
;         float t[11];
; #pragma unroll
;         for (int i = 0; i < 5; ++i) t[i] = max3f(st[0][3 * i], st[0][3 * i + 1], st[0][3 * i + 2]);
; #pragma unroll
;         for (int i = 0; i < 5; ++i) t[5 + i] = max3f(st[1][3 * i], st[1][3 * i + 1], st[1][3 * i + 2]);
;         t[10] = fmaxf(st[0][15], st[1][15]);
;         const float u0 = max3f(t[0], t[1], t[2]), u1 = max3f(t[3], t[4], t[5]), u2 = max3f(t[6], t[7], t[8]);
;         mx = max3f(max3f(u0, u1, u2), t[9], t[10]);
;     }
;     mx = xor32_max(mx);
;     if (tt == 0 || __builtin_amdgcn_ballot_w64(mx > 8.0f) != 0ull) {
;         const float delta = tt == 0 ? mx : fmaxf(mx, 0.f);
;         const float alpha = __builtin_amdgcn_exp2f(-delta);
;         m += delta;
;         l *= alpha;
; #pragma unroll
;         for (int d = 0; d < 4; ++d) O[d] = O[d] * alpha;
; #pragma unroll
;         for (int k2 = 0; k2 < 2; ++k2) st[k2] = st[k2] - delta;
;     }
; #pragma unroll
;     for (int k2 = 0; k2 < 2; ++k2)
; #pragma unroll
;         for (int i = 0; i < 16; ++i) st[k2][i] = __builtin_amdgcn_exp2f(st[k2][i]);
;     {
;         const f32x16 sv = st[0] + st[1];
;         const float ps = (((sv[0] + sv[1]) + (sv[2] + sv[3])) + ((sv[4] + sv[5]) + (sv[6] + sv[7]))) + (((sv[8] + sv[9]) + (sv[10] + sv[11])) + ((sv[12] + sv[13]) + (sv[14] + sv[15])));
;         l += ps;
;     }
; #pragma unroll
;     for (int k4 = 0; k4 < 4; ++k4) {
	v_lshl_add_u64 v[184:185], v[82:83], 0, s[90:91]
	global_load_dwordx4 v[116:119], v[184:185], off
	s_nop 0
	v_lshl_add_u64 v[184:185], v[184:185], 0, s[92:93]
	global_load_dwordx4 v[120:123], v[184:185], off
	s_nop 0
	v_lshl_add_u64 v[184:185], v[84:85], 0, s[88:89]
	global_load_dwordx4 v[124:127], v[184:185], off
	s_nop 0
	v_add_co_u32_e32 v184, vcc, 0x80000, v184
	s_nop 1
	v_addc_co_u32_e32 v185, vcc, 0, v185, vcc
	global_load_dwordx4 v[128:131], v[184:185], off
	ds_read_b128 v[26:29], v1 offset:8704
	ds_read_b128 v[30:33], v1 offset:8736
	ds_read_b128 v[34:37], v1 offset:8768
	ds_read_b128 v[38:41], v1 offset:8800
	v_mov_b32_e32 v10, v0
	v_mov_b32_e32 v11, v0
	v_mov_b32_e32 v12, v0
	v_mov_b32_e32 v13, v0
	v_mov_b32_e32 v14, v0
	v_mov_b32_e32 v15, v0
	v_mov_b32_e32 v1, v0
	v_mov_b32_e32 v2, v0
	v_mov_b32_e32 v3, v0
	v_mov_b32_e32 v4, v0
	v_mov_b32_e32 v5, v0
	v_mov_b32_e32 v6, v0
	v_mov_b32_e32 v7, v0
	v_mov_b32_e32 v8, v0
	v_mov_b32_e32 v9, v0
	v_mov_b64_e32 v[24:25], v[14:15]
	v_mov_b64_e32 v[22:23], v[12:13]
	v_mov_b64_e32 v[20:21], v[10:11]
	v_mov_b64_e32 v[18:19], v[8:9]
	v_mov_b64_e32 v[16:17], v[6:7]
	v_mov_b64_e32 v[14:15], v[4:5]
	v_mov_b64_e32 v[12:13], v[2:3]
	v_mov_b64_e32 v[10:11], v[0:1]
	s_waitcnt lgkmcnt(3)
	s_nop 0
	v_mfma_f32_32x32x16_bf16 v[10:25], v[26:29], v[100:103], v[10:25]
	s_waitcnt lgkmcnt(2)
	v_mfma_f32_32x32x16_bf16 v[10:25], v[30:33], v[104:107], v[10:25]
	s_waitcnt lgkmcnt(1)
	v_mfma_f32_32x32x16_bf16 v[10:25], v[34:37], v[108:111], v[10:25]
	v_max3_f32 v1, v188, v188, v188
	s_nop 0
	v_max3_f32 v2, v1, v1, v1
	s_waitcnt lgkmcnt(0)
	v_mfma_f32_32x32x16_bf16 v[10:25], v[38:41], v[112:115], v[10:25]
	v_max3_f32 v3, v188, v188, v18
	v_max3_f32 v4, v19, v20, v21
	v_max3_f32 v5, v22, v23, v24
	s_nop 0
	v_max3_f32 v1, v1, v3, v4
	s_nop 10
	v_max_f32_e32 v6, v25, v25
	v_max3_f32 v1, v2, v2, v1
	v_max_f32_e32 v6, 0xff800000, v6
	v_max3_f32 v1, v1, v5, v6
	s_nop 0
	v_mov_b32_e32 v2, v1
	s_nop 1
	v_permlane32_swap_b32_e32 v1, v2
	v_max_f32_e32 v2, v2, v2
	v_max_f32_e32 v1, v1, v1
	v_max_f32_e32 v86, v1, v2
	v_sub_f32_e32 v1, 0xff800000, v86
	v_sub_f32_e32 v19, v19, v86
	v_sub_f32_e32 v26, v18, v86
	v_sub_f32_e32 v21, v21, v86
	v_sub_f32_e32 v20, v20, v86
	v_exp_f32_e32 v18, v1
	v_exp_f32_e32 v26, v26
	v_exp_f32_e32 v27, v19
	v_sub_f32_e32 v23, v23, v86
	v_sub_f32_e32 v22, v22, v86
	v_exp_f32_e32 v28, v20
	v_exp_f32_e32 v29, v21
	v_sub_f32_e32 v25, v25, v86
	v_sub_f32_e32 v24, v24, v86
	v_exp_f32_e32 v30, v22
	v_exp_f32_e32 v31, v23
	v_exp_f32_e32 v32, v24
	v_exp_f32_e32 v33, v25
	v_pk_add_f32 v[34:35], v[18:19], v[26:27] op_sel_hi:[0,1]
	v_add_f32_e32 v36, v18, v18
	v_pk_add_f32 v[24:25], v[18:19], v[28:29] op_sel_hi:[0,1]
	v_mov_b32_e32 v37, v34
	v_mov_b32_e32 v34, v36
	v_pk_add_f32 v[22:23], v[18:19], v[30:31] op_sel_hi:[0,1]
	v_pk_add_f32 v[34:35], v[36:37], v[34:35]
	v_mov_b32_e32 v37, v24
	v_mov_b32_e32 v24, v36
	v_pk_add_f32 v[20:21], v[18:19], v[32:33] op_sel_hi:[0,1]
	v_pk_add_f32 v[24:25], v[36:37], v[24:25]
	v_mov_b32_e32 v37, v22
	v_mov_b32_e32 v22, v36
	v_pk_add_f32 v[22:23], v[36:37], v[22:23]
	v_mov_b32_e32 v37, v20
	v_mov_b32_e32 v20, v36
	v_pk_add_f32 v[20:21], v[36:37], v[20:21]
	v_cvt_pk_bf16_f32 v88, v18, v18
	v_lshlrev_b32_e32 v18, 7, v146
	v_pk_add_f32 v[24:25], v[34:35], v[24:25]
	v_pk_add_f32 v[20:21], v[22:23], v[20:21]
	v_sub_u32_e32 v18, v42, v18
	v_pk_add_f32 v[20:21], v[24:25], v[20:21]
	v_add_u32_e32 v185, v18, v98
	v_add_f32_e32 v1, v20, v21
	ds_read_b128 v[18:21], v185 offset:17408
	ds_read_b128 v[22:25], v185 offset:22016
	ds_read_b128 v[92:95], v185 offset:26624
	ds_read_b128 v[142:145], v185 offset:31232
	v_exp_f32_e64 v184, -v86
	v_mov_b32_e32 v89, v88
	v_mov_b32_e32 v90, v88
	v_mov_b32_e32 v91, v88
	v_mul_f32_e32 v2, 0, v184
	v_mov_b32_e32 v3, v2
	v_mov_b32_e32 v4, v2
	v_mov_b32_e32 v5, v2
	v_mov_b32_e32 v6, v2
	v_mov_b32_e32 v7, v2
	v_mov_b32_e32 v8, v2
	v_mov_b32_e32 v9, v2
	v_mov_b32_e32 v10, v2
	v_mov_b32_e32 v11, v2
	v_mov_b32_e32 v12, v2
	v_mov_b32_e32 v13, v2
	v_mov_b32_e32 v14, v2
	v_mov_b32_e32 v15, v2
	v_mov_b32_e32 v16, v2
	v_mov_b32_e32 v17, v2
	v_cvt_pk_bf16_f32 v156, v26, v27
	v_cvt_pk_bf16_f32 v157, v28, v29
	v_cvt_pk_bf16_f32 v158, v30, v31
	v_cvt_pk_bf16_f32 v159, v32, v33
	ds_read_b128 v[160:163], v185 offset:17440
	ds_read_b128 v[164:167], v185 offset:22048
	ds_read_b128 v[168:171], v185 offset:26656
	ds_read_b128 v[172:175], v185 offset:31264
	s_waitcnt lgkmcnt(7)
	v_mfma_f32_32x32x16_bf16 v[50:65], v[18:21], v[88:91], v[2:17]
	s_waitcnt lgkmcnt(6)
	v_mfma_f32_32x32x16_bf16 v[34:49], v[22:25], v[88:91], v[2:17]
	s_waitcnt lgkmcnt(5)
	v_mfma_f32_32x32x16_bf16 v[18:33], v[92:95], v[88:91], v[2:17]
	s_waitcnt lgkmcnt(4)
	v_mfma_f32_32x32x16_bf16 v[2:17], v[142:145], v[88:91], v[2:17]
	ds_read_b128 v[92:95], v185 offset:17472
	ds_read_b128 v[142:145], v185 offset:22080
	ds_read_b128 v[176:179], v185 offset:26688
	ds_read_b128 v[180:183], v185 offset:31296
	s_waitcnt lgkmcnt(7)
	v_mfma_f32_32x32x16_bf16 v[50:65], v[160:163], v[88:91], v[50:65]
	s_waitcnt lgkmcnt(6)
	v_mfma_f32_32x32x16_bf16 v[34:49], v[164:167], v[88:91], v[34:49]
	s_waitcnt lgkmcnt(5)
	v_mfma_f32_32x32x16_bf16 v[18:33], v[168:171], v[88:91], v[18:33]
	s_waitcnt lgkmcnt(4)
	v_mfma_f32_32x32x16_bf16 v[2:17], v[172:175], v[88:91], v[2:17]
	ds_read_b128 v[160:163], v185 offset:17504
	ds_read_b128 v[164:167], v185 offset:22112
	ds_read_b128 v[168:171], v185 offset:26720
	ds_read_b128 v[172:175], v185 offset:31328
	s_waitcnt lgkmcnt(7)
	v_mfma_f32_32x32x16_bf16 v[50:65], v[92:95], v[88:91], v[50:65]
	s_waitcnt lgkmcnt(6)
	v_mfma_f32_32x32x16_bf16 v[34:49], v[142:145], v[88:91], v[34:49]
	s_waitcnt lgkmcnt(5)
	v_mfma_f32_32x32x16_bf16 v[18:33], v[176:179], v[88:91], v[18:33]
	s_waitcnt lgkmcnt(4)
	v_mfma_f32_32x32x16_bf16 v[2:17], v[180:183], v[88:91], v[2:17]
	s_waitcnt lgkmcnt(3)
	v_mfma_f32_32x32x16_bf16 v[50:65], v[160:163], v[156:159], v[50:65]
	s_waitcnt vmcnt(7)
	ds_write_b128 v87, v[74:77] offset:35840
	s_waitcnt vmcnt(5)
	ds_write_b128 v96, v[78:81] offset:35840
	v_add_u32_e32 v74, 0xd000, v97
	ds_write2_b64 v74, v[70:71], v[72:73] offset1:2
	v_add_u32_e32 v70, 0xd000, v155
	v_fmac_f32_e32 v1, 0, v184
	s_cmpk_gt_u32 s4, 0x7f
	s_waitcnt vmcnt(4)
	ds_write2_b64 v70, v[66:67], v[68:69] offset1:2
	s_waitcnt lgkmcnt(6)
	v_mfma_f32_32x32x16_bf16 v[34:49], v[164:167], v[156:159], v[34:49]
	s_waitcnt lgkmcnt(0)
	s_barrier
; #define MFMA32(a, b, c) __builtin_amdgcn_mfma_f32_32x32x16_bf16((a), (b), (c), 0, 0, 0)
; DI void attn_s(const unsigned char* sK, int tt, int qb, int qs, int sub, int l31, int h,
;                const bf16x8 (&qf)[4], f32x16 (&O)[4], float& m, float& l, bf16x8 (&pb)[4]) {
;     ...
;     for (int k2 = 0; k2 < 2; ++k2)
; #pragma unroll
;         for (int i = 0; i < 16; ++i) st[k2][i] = -m;
;     {
;         const unsigned char* kb = sK + l31 * A_KROWB + (sub * 64 + 8 * h) * 2;
;         bf16x8 ka[4], kc[4];
; #pragma unroll
;         for (int i = 0; i < 4; ++i) ka[i] = *(const bf16x8*)(kb + (i & 1) * 32 * A_KROWB + (i >> 1) * 32);
;         __builtin_amdgcn_sched_barrier(0);
; #pragma unroll
;         for (int i = 0; i < 4; ++i) kc[i] = *(const bf16x8*)(kb + (i & 1) * 32 * A_KROWB + (2 + (i >> 1)) * 32);
;         __builtin_amdgcn_sched_barrier(0);
; #pragma unroll
;         for (int i = 0; i < 4; ++i) st[i & 1] = MFMA32(ka[i], qf[i >> 1], st[i & 1]);
;         __builtin_amdgcn_sched_barrier(0);
; #pragma unroll
;         for (int i = 0; i < 4; ++i) st[i & 1] = MFMA32(kc[i], qf[2 + (i >> 1)], st[i & 1]);
	v_mfma_f32_32x32x16_bf16 v[18:33], v[168:171], v[156:159], v[18:33]
	v_mfma_f32_32x32x16_bf16 v[2:17], v[172:175], v[156:159], v[2:17]
	s_cbranch_scc1 .LBB0_1824
	s_lshr_b32 s4, s4, 1
	s_lshl_b32 s5, s5, 1
	s_and_b32 s4, s4, 0x7ffffff8
	s_lshl_b32 s0, s0, 1
	s_or_b32 s4, s5, s4
	v_mul_u32_u24_e32 v155, 0x110, v146
	v_mul_u32_u24_e32 v156, 0x90, v146
	s_mov_b32 s13, 1
	s_add_i32 s6, s0, 3
	v_lshl_add_u64 v[142:143], v[84:85], 0, s[88:89]
	v_lshl_add_u64 v[142:143], v[142:143], 0, s[88:89]
	v_add_f32_e32 v157, 0, v86
	v_lshl_add_u64 v[144:145], v[82:83], 0, s[90:91]
	v_lshl_add_u64 v[144:145], v[144:145], 0, s[90:91]
	s_mov_b32 s7, 2
	v_lshl_or_b32 v158, v149, 2, 59
	s_sub_i32 s11, 0, s4
	s_movk_i32 s12, 0xffc0
	v_readfirstlane_b32 s99, v147
	s_cmp_eq_u32 s99, 1
	s_cbranch_scc0 .Lpipe_nooffs
	s_barrier
.Lpipe_nooffs:
	s_barrier
	s_mul_i32 s98, s13, 0x8c00
	s_add_i32 s98, s98, 0
	v_add3_u32 v67, s98, v155, v154
	ds_read_b128 v[160:163], v67
	ds_read_b128 v[164:167], v67 offset:32
	ds_read_b128 v[168:171], v67 offset:8704
	ds_read_b128 v[172:175], v67 offset:8736
	v_xor_b32_e32 v66, 0x80000000, v157
	ds_read_b128 v[176:179], v67 offset:64
	ds_read_b128 v[180:183], v67 offset:96
	ds_read_b128 v[192:195], v67 offset:8768
	ds_read_b128 v[196:199], v67 offset:8800
	v_mov_b32_e32 v67, v66
	v_mov_b32_e32 v68, v66
	v_mov_b32_e32 v69, v66
	v_mov_b32_e32 v70, v66
	v_mov_b32_e32 v71, v66
	v_mov_b32_e32 v72, v66
	v_mov_b32_e32 v73, v66
	v_mov_b32_e32 v74, v66
	v_mov_b32_e32 v75, v66
	v_mov_b32_e32 v76, v66
	v_mov_b32_e32 v77, v66
	v_mov_b32_e32 v78, v66
	v_mov_b32_e32 v79, v66
	v_mov_b32_e32 v80, v66
	v_mov_b32_e32 v81, v66
	s_waitcnt lgkmcnt(7)
	s_nop 0
	v_mfma_f32_32x32x16_bf16 v[82:97], v[160:163], v[100:103], v[66:81]
	s_waitcnt lgkmcnt(5)
	v_mfma_f32_32x32x16_bf16 v[66:81], v[168:171], v[100:103], v[66:81]
	v_mfma_f32_32x32x16_bf16 v[82:97], v[164:167], v[104:107], v[82:97]
	s_waitcnt lgkmcnt(4)
	v_mfma_f32_32x32x16_bf16 v[66:81], v[172:175], v[104:107], v[66:81]
	s_waitcnt lgkmcnt(3)
	v_mfma_f32_32x32x16_bf16 v[82:97], v[176:179], v[108:111], v[82:97]
	s_waitcnt lgkmcnt(1)
	v_mfma_f32_32x32x16_bf16 v[66:81], v[192:195], v[108:111], v[66:81]
	v_mfma_f32_32x32x16_bf16 v[82:97], v[180:183], v[112:115], v[82:97]
	s_waitcnt lgkmcnt(0)
	v_mfma_f32_32x32x16_bf16 v[66:81], v[196:199], v[112:115], v[66:81]
	s_add_i32 s14, s12, 0x42
	s_cmp_ge_i32 s14, s6
	s_cbranch_scc1 .Lpipe_nostage_p
	s_mul_i32 s4, s7, 0x8c00
	s_add_i32 s4, s4, 0
	v_add_u32_e32 v184, s4, v140
	v_add_u32_e32 v185, v184, v139
	v_add_u32_e32 v184, v184, v141
	s_waitcnt vmcnt(3)
	ds_write_b128 v185, v[116:119]
	s_waitcnt vmcnt(2)
	ds_write_b128 v184, v[120:123]
	v_add3_u32 v184, s4, v150, v151
	v_add_u32_e32 v185, v184, v152
	v_add_u32_e32 v184, v184, v153
	v_add_u32_e32 v185, 0x4000, v185
	v_add_u32_e32 v184, 0x4000, v184
	s_waitcnt vmcnt(1)
	ds_write2_b64 v185, v[124:125], v[126:127] offset0:128 offset1:130
	s_waitcnt vmcnt(0)
	ds_write2_b64 v184, v[128:129], v[130:131] offset0:128 offset1:130
	s_add_i32 s14, s12, 0x43
	s_cmp_ge_i32 s14, s6
	s_cbranch_scc1 .Lpipe_nostage_p
	v_add_co_u32_e32 v184, vcc, 0x10000, v144
	global_load_dwordx4 v[116:119], v[144:145], off
	s_nop 0
	v_addc_co_u32_e32 v185, vcc, 0, v145, vcc
	global_load_dwordx4 v[120:123], v[184:185], off
	global_load_dwordx4 v[124:127], v[142:143], off
	v_add_co_u32_e32 v184, vcc, 0x80000, v142
	v_lshl_add_u64 v[144:145], v[144:145], 0, s[90:91]
	s_nop 0
	v_addc_co_u32_e32 v185, vcc, 0, v143, vcc
	global_load_dwordx4 v[128:131], v[184:185], off
	v_lshl_add_u64 v[142:143], v[142:143], 0, s[88:89]

; DI void attn_s(const unsigned char* sK, int tt, int qb, int qs, int sub, int l31, int h,
;                const bf16x8 (&qf)[4], f32x16 (&O)[4], float& m, float& l, bf16x8 (&pb)[4]) {
;     ...
;     } else if (tt >= 2 * qb + 1) {
;         const int kbase = (tt - 1) * 64 + 4 * h;
; #pragma unroll
;         for (int k2 = 0; k2 < 2; ++k2)
; #pragma unroll
;             for (int i = 0; i < 16; ++i) {
;                 const int key = kbase + k2 * 32 + (i & 3) + 8 * (i >> 2);
;                 if (key > qs) st[k2][i] = -INFINITY;
;             }
;     }
.Lpipe_loop:
	s_add_i32 s14, s12, 0x41
	s_cmp_le_i32 s14, s0
	s_cbranch_scc1 .Lpipe_nomask_l
	v_subrev_u32_e32 v159, 59, v158
	v_cmp_gt_i32_e32 vcc, v159, v138
	s_nop 6
	v_cndmask_b32_e32 v160, v82, v188, vcc
	v_cmp_lt_i32_e32 vcc, v159, v138
	v_subrev_u32_e32 v159, 57, v158
	s_nop 0
	v_cndmask_b32_e32 v82, v160, v82, vcc
	v_cndmask_b32_e32 v83, v188, v83, vcc
	v_cmp_le_i32_e32 vcc, v159, v138
	v_subrev_u32_e32 v159, 56, v158
	s_nop 0
	v_cndmask_b32_e32 v84, v188, v84, vcc
	v_cmp_le_i32_e32 vcc, v159, v138
	v_subrev_u32_e32 v159, 51, v158
	s_nop 0
	v_cndmask_b32_e32 v85, v188, v85, vcc
	v_cmp_le_i32_e32 vcc, v159, v138
	v_subrev_u32_e32 v159, 50, v158
	s_nop 0
	v_cndmask_b32_e32 v86, v188, v86, vcc
	v_cmp_le_i32_e32 vcc, v159, v138
	v_subrev_u32_e32 v159, 49, v158
	s_nop 0
	v_cndmask_b32_e32 v87, v188, v87, vcc
	v_cmp_le_i32_e32 vcc, v159, v138
	v_subrev_u32_e32 v159, 48, v158
	s_nop 0
	v_cndmask_b32_e32 v88, v188, v88, vcc
	v_cmp_le_i32_e32 vcc, v159, v138
	v_subrev_u32_e32 v159, 43, v158
	s_nop 0
	v_cndmask_b32_e32 v89, v188, v89, vcc
	v_cmp_le_i32_e32 vcc, v159, v138
	v_subrev_u32_e32 v159, 42, v158
	s_nop 0
	v_cndmask_b32_e32 v90, v188, v90, vcc
	v_cmp_le_i32_e32 vcc, v159, v138
	v_subrev_u32_e32 v159, 41, v158
	s_nop 0
	v_cndmask_b32_e32 v91, v188, v91, vcc
	v_cmp_le_i32_e32 vcc, v159, v138
	v_subrev_u32_e32 v159, 40, v158
	s_nop 0
	v_cndmask_b32_e32 v92, v188, v92, vcc
	v_cmp_le_i32_e32 vcc, v159, v138
	v_subrev_u32_e32 v159, 35, v158
	s_nop 0
	v_cndmask_b32_e32 v93, v188, v93, vcc
	v_cmp_le_i32_e32 vcc, v159, v138
	v_subrev_u32_e32 v159, 34, v158
	s_nop 0
	v_cndmask_b32_e32 v94, v188, v94, vcc
	v_cmp_le_i32_e32 vcc, v159, v138
	v_subrev_u32_e32 v159, 33, v158
	s_nop 0
	v_cndmask_b32_e32 v95, v188, v95, vcc
	v_cmp_le_i32_e32 vcc, v159, v138
	v_subrev_u32_e32 v159, 32, v158
	s_nop 0
	v_cndmask_b32_e32 v96, v188, v96, vcc
	v_cmp_le_i32_e32 vcc, v159, v138
	v_subrev_u32_e32 v159, 27, v158
	s_nop 0
	v_cndmask_b32_e32 v97, v188, v97, vcc
	v_cmp_le_i32_e32 vcc, v159, v138
	v_subrev_u32_e32 v159, 26, v158
	s_nop 0
	v_cndmask_b32_e32 v66, v188, v66, vcc
	v_cmp_le_i32_e32 vcc, v159, v138
	v_subrev_u32_e32 v159, 25, v158
	s_nop 0
	v_cndmask_b32_e32 v67, v188, v67, vcc
	v_cmp_le_i32_e32 vcc, v159, v138
	v_subrev_u32_e32 v159, 24, v158
	s_nop 0
	v_cndmask_b32_e32 v68, v188, v68, vcc
	v_cmp_le_i32_e32 vcc, v159, v138
	v_subrev_u32_e32 v159, 19, v158
	s_nop 0
	v_cndmask_b32_e32 v69, v188, v69, vcc
	v_cmp_le_i32_e32 vcc, v159, v138
	v_subrev_u32_e32 v159, 18, v158
	s_nop 0
	v_cndmask_b32_e32 v70, v188, v70, vcc
	v_cmp_le_i32_e32 vcc, v159, v138
	v_subrev_u32_e32 v159, 17, v158
	s_nop 0
	v_cndmask_b32_e32 v71, v188, v71, vcc
	v_cmp_le_i32_e32 vcc, v159, v138
	v_add_u32_e32 v159, -16, v158
	s_nop 0
	v_cndmask_b32_e32 v72, v188, v72, vcc
	v_cmp_le_i32_e32 vcc, v159, v138
	v_add_u32_e32 v159, -11, v158
	s_nop 0
	v_cndmask_b32_e32 v73, v188, v73, vcc
	v_cmp_le_i32_e32 vcc, v159, v138
	v_add_u32_e32 v159, -10, v158
	s_nop 0
	v_cndmask_b32_e32 v74, v188, v74, vcc
	v_cmp_le_i32_e32 vcc, v159, v138
	v_add_u32_e32 v159, -9, v158
	s_nop 0
	v_cndmask_b32_e32 v75, v188, v75, vcc
	v_cmp_le_i32_e32 vcc, v159, v138
	v_add_u32_e32 v159, -8, v158
	s_nop 0
	v_cndmask_b32_e32 v76, v188, v76, vcc
	v_cmp_le_i32_e32 vcc, v159, v138
	v_add_u32_e32 v159, -3, v158
	s_nop 0
	v_cndmask_b32_e32 v77, v188, v77, vcc
	v_cmp_le_i32_e32 vcc, v159, v138
	v_add_u32_e32 v159, -2, v158
	s_nop 0
	v_cndmask_b32_e32 v78, v188, v78, vcc
	v_cmp_le_i32_e32 vcc, v159, v138
	v_add_u32_e32 v159, -1, v158
	s_nop 0
	v_cndmask_b32_e32 v79, v188, v79, vcc
	v_cmp_le_i32_e32 vcc, v159, v138
	s_nop 1
	v_cndmask_b32_e32 v80, v188, v80, vcc
	v_cmp_le_i32_e32 vcc, v158, v138
	s_nop 1
	v_cndmask_b32_e32 v81, v188, v81, vcc

; #define MFMA32(a, b, c) __builtin_amdgcn_mfma_f32_32x32x16_bf16((a), (b), (c), 0, 0, 0)
; DI void attn_s(const unsigned char* sK, int tt, int qb, int qs, int sub, int l31, int h,
;                const bf16x8 (&qf)[4], f32x16 (&O)[4], float& m, float& l, bf16x8 (&pb)[4]) {
;     ...
; #pragma unroll
;     for (int k2 = 0; k2 < 2; ++k2)
; #pragma unroll
;         for (int i = 0; i < 16; ++i) st[k2][i] = __builtin_amdgcn_exp2f(st[k2][i]);
;     {
;         const f32x16 sv = st[0] + st[1];
;         const float ps = (((sv[0] + sv[1]) + (sv[2] + sv[3])) + ((sv[4] + sv[5]) + (sv[6] + sv[7]))) + (((sv[8] + sv[9]) + (sv[10] + sv[11])) + ((sv[12] + sv[13]) + (sv[14] + sv[15])));
;         l += ps;
;     }
; #pragma unroll
;     for (int k4 = 0; k4 < 4; ++k4) {
;         const int k2 = k4 >> 1, o8 = 8 * (k4 & 1);
;         u32x4 pk;
;         pk.x = pk2(st[k2][o8 + 0], st[k2][o8 + 1]); pk.y = pk2(st[k2][o8 + 2], st[k2][o8 + 3]);
;         pk.z = pk2(st[k2][o8 + 4], st[k2][o8 + 5]); pk.w = pk2(st[k2][o8 + 6], st[k2][o8 + 7]);
;         pb[k4] = __builtin_bit_cast(bf16x8, pk);
;     }
; DI void attn_pv(const unsigned char* sV, int l31, int h, const bf16x8 (&pb)[4], f32x16 (&O)[4]) {
;     {
;         const unsigned char* vb = sV + l31 * A_VROWB + 16 * h;
;         bf16x8 va[4], vc[4];
; #pragma unroll
;         for (int d = 0; d < 4; ++d) va[d] = *(const bf16x8*)(vb + d * 32 * A_VROWB);
;         __builtin_amdgcn_sched_barrier(0);
; #pragma unroll
;         for (int d = 0; d < 4; ++d) vc[d] = *(const bf16x8*)(vb + d * 32 * A_VROWB + 32);
;         __builtin_amdgcn_sched_barrier(0);
; #pragma unroll
;         for (int d = 0; d < 4; ++d) O[d] = MFMA32(va[d], pb[0], O[d]);
;         __builtin_amdgcn_sched_barrier(0);
; #pragma unroll
;         for (int d = 0; d < 4; ++d) va[d] = *(const bf16x8*)(vb + d * 32 * A_VROWB + 64);
;         __builtin_amdgcn_sched_barrier(0);
; #pragma unroll
;         for (int d = 0; d < 4; ++d) O[d] = MFMA32(vc[d], pb[1], O[d]);
;         __builtin_amdgcn_sched_barrier(0);
; #pragma unroll
;         for (int d = 0; d < 4; ++d) vc[d] = *(const bf16x8*)(vb + d * 32 * A_VROWB + 96);
;         __builtin_amdgcn_sched_barrier(0);
; #pragma unroll
;         for (int d = 0; d < 4; ++d) O[d] = MFMA32(va[d], pb[2], O[d]);
;         __builtin_amdgcn_sched_barrier(0);
; #pragma unroll
;         for (int d = 0; d < 4; ++d) O[d] = MFMA32(vc[d], pb[3], O[d]);
.Lpipe_norescale_l:
	v_exp_f32_e32 v82, v82
	v_exp_f32_e32 v83, v83
	v_exp_f32_e32 v84, v84
	v_exp_f32_e32 v85, v85
	v_exp_f32_e32 v86, v86
	v_exp_f32_e32 v87, v87
	v_exp_f32_e32 v88, v88
	v_exp_f32_e32 v89, v89
	v_exp_f32_e32 v90, v90
	v_exp_f32_e32 v91, v91
	v_exp_f32_e32 v92, v92
	v_exp_f32_e32 v93, v93
	v_exp_f32_e32 v94, v94
	v_exp_f32_e32 v95, v95
	v_exp_f32_e32 v96, v96
	v_exp_f32_e32 v97, v97
	v_exp_f32_e32 v66, v66
	v_exp_f32_e32 v67, v67
	v_exp_f32_e32 v68, v68
	v_exp_f32_e32 v69, v69
	v_exp_f32_e32 v70, v70
	v_exp_f32_e32 v71, v71
	v_exp_f32_e32 v72, v72
	v_exp_f32_e32 v73, v73
	v_exp_f32_e32 v74, v74
	v_exp_f32_e32 v75, v75
	v_exp_f32_e32 v76, v76
	v_exp_f32_e32 v77, v77
	v_exp_f32_e32 v78, v78
	v_exp_f32_e32 v79, v79
	v_exp_f32_e32 v80, v80
	v_exp_f32_e32 v81, v81
	v_cvt_pk_bf16_f32 v216, v82, v83
	v_cvt_pk_bf16_f32 v217, v84, v85
	v_cvt_pk_bf16_f32 v218, v86, v87
	v_cvt_pk_bf16_f32 v219, v88, v89
	v_cvt_pk_bf16_f32 v220, v90, v91
	v_cvt_pk_bf16_f32 v221, v92, v93
	v_cvt_pk_bf16_f32 v222, v94, v95
	v_cvt_pk_bf16_f32 v223, v96, v97
	v_cvt_pk_bf16_f32 v224, v66, v67
	v_cvt_pk_bf16_f32 v225, v68, v69
	v_cvt_pk_bf16_f32 v226, v70, v71
	v_cvt_pk_bf16_f32 v227, v72, v73
	v_cvt_pk_bf16_f32 v228, v74, v75
	v_cvt_pk_bf16_f32 v229, v76, v77
	v_cvt_pk_bf16_f32 v230, v78, v79
	v_cvt_pk_bf16_f32 v231, v80, v81
	v_pk_add_f32 v[68:69], v[84:85], v[68:69]
	v_pk_add_f32 v[66:67], v[82:83], v[66:67]
	v_pk_add_f32 v[72:73], v[88:89], v[72:73]
	v_pk_add_f32 v[70:71], v[86:87], v[70:71]
	v_add_f32_e32 v66, v66, v67
	v_add_f32_e32 v67, v68, v69
	v_add_f32_e32 v66, v66, v67
	v_add_f32_e32 v67, v70, v71
	v_add_f32_e32 v68, v72, v73
	v_pk_add_f32 v[76:77], v[92:93], v[76:77]
	v_pk_add_f32 v[74:75], v[90:91], v[74:75]
	v_add_f32_e32 v67, v67, v68
	v_pk_add_f32 v[80:81], v[96:97], v[80:81]
	v_pk_add_f32 v[78:79], v[94:95], v[78:79]
	v_add_f32_e32 v66, v66, v67
	v_add_f32_e32 v67, v74, v75
	v_add_f32_e32 v68, v76, v77
	v_add_f32_e32 v67, v67, v68
	v_add_f32_e32 v68, v78, v79
	v_add_f32_e32 v69, v80, v81
	v_add_f32_e32 v68, v68, v69
	v_add_f32_e32 v67, v67, v68
	v_add_f32_e32 v66, v66, v67
	v_add_f32_e32 v1, v1, v66
	v_add_u32_e32 v158, 64, v158
	v_add3_u32 v191, s98, v156, v98
	ds_read_b128 v[172:175], v191 offset:17408
	ds_read_b128 v[176:179], v191 offset:22016
	ds_read_b128 v[180:183], v191 offset:26624
	ds_read_b128 v[192:195], v191 offset:31232
	ds_read_b128 v[200:203], v191 offset:17440
	ds_read_b128 v[204:207], v191 offset:22048
	ds_read_b128 v[208:211], v191 offset:26656
	ds_read_b128 v[212:215], v191 offset:31264
	s_mov_b32 s13, s7
	s_add_i32 s4, s7, 1
	s_cmp_lg_u32 s7, 2
	s_cselect_b32 s7, s4, 0
	s_add_i32 s12, s12, 1
	s_cmp_eq_u32 s11, s12
	s_cbranch_scc1 .Lpipe_final
	s_barrier
	s_mul_i32 s98, s13, 0x8c00
	v_add3_u32 v185, s98, v155, v154
	ds_read_b128 v[160:163], v185
	ds_read_b128 v[164:167], v185 offset:32
	ds_read_b128 v[168:171], v185 offset:8704
	ds_read_b128 v[196:199], v185 offset:8736
	s_waitcnt lgkmcnt(11)
	v_mfma_f32_32x32x16_bf16 v[50:65], v[172:175], v[216:219], v[50:65]
	s_waitcnt lgkmcnt(10)
	v_mfma_f32_32x32x16_bf16 v[34:49], v[176:179], v[216:219], v[34:49]
	s_waitcnt lgkmcnt(9)
	v_mfma_f32_32x32x16_bf16 v[18:33], v[180:183], v[216:219], v[18:33]
	s_waitcnt lgkmcnt(8)
	v_mfma_f32_32x32x16_bf16 v[2:17], v[192:195], v[216:219], v[2:17]
	ds_read_b128 v[172:175], v185 offset:64
	ds_read_b128 v[176:179], v185 offset:96
	ds_read_b128 v[180:183], v185 offset:8768
	ds_read_b128 v[192:195], v185 offset:8800
	v_xor_b32_e32 v66, 0x80000000, v157
	v_mov_b32_e32 v67, v66
	v_mov_b32_e32 v68, v66
	v_mov_b32_e32 v69, v66
	v_mov_b32_e32 v70, v66
	v_mov_b32_e32 v71, v66
	v_mov_b32_e32 v72, v66
	v_mov_b32_e32 v73, v66
	v_mov_b32_e32 v74, v66
	v_mov_b32_e32 v75, v66
	v_mov_b32_e32 v76, v66
	v_mov_b32_e32 v77, v66
	v_mov_b32_e32 v78, v66
	v_mov_b32_e32 v79, v66
	v_mov_b32_e32 v80, v66
	v_mov_b32_e32 v81, v66
	s_waitcnt lgkmcnt(11)
	v_mfma_f32_32x32x16_bf16 v[50:65], v[200:203], v[220:223], v[50:65]
	s_waitcnt lgkmcnt(10)
	v_mfma_f32_32x32x16_bf16 v[34:49], v[204:207], v[220:223], v[34:49]
	s_waitcnt lgkmcnt(9)
	v_mfma_f32_32x32x16_bf16 v[18:33], v[208:211], v[220:223], v[18:33]
	s_waitcnt lgkmcnt(8)
	v_mfma_f32_32x32x16_bf16 v[2:17], v[212:215], v[220:223], v[2:17]
	ds_read_b128 v[200:203], v191 offset:17472
	ds_read_b128 v[204:207], v191 offset:22080
	ds_read_b128 v[208:211], v191 offset:26688
	ds_read_b128 v[212:215], v191 offset:31296
	s_waitcnt lgkmcnt(11)
	v_mfma_f32_32x32x16_bf16 v[82:97], v[160:163], v[100:103], v[66:81]
	s_waitcnt lgkmcnt(9)
	v_mfma_f32_32x32x16_bf16 v[66:81], v[168:171], v[100:103], v[66:81]
	v_mfma_f32_32x32x16_bf16 v[82:97], v[164:167], v[104:107], v[82:97]
	s_waitcnt lgkmcnt(8)
	v_mfma_f32_32x32x16_bf16 v[66:81], v[196:199], v[104:107], v[66:81]
	ds_read_b128 v[160:163], v191 offset:17504
	ds_read_b128 v[164:167], v191 offset:22112
	ds_read_b128 v[168:171], v191 offset:26720
	ds_read_b128 v[196:199], v191 offset:31328
	s_waitcnt lgkmcnt(11)
	v_mfma_f32_32x32x16_bf16 v[82:97], v[172:175], v[108:111], v[82:97]
	s_waitcnt lgkmcnt(9)
	v_mfma_f32_32x32x16_bf16 v[66:81], v[180:183], v[108:111], v[66:81]
	v_mfma_f32_32x32x16_bf16 v[82:97], v[176:179], v[112:115], v[82:97]
	s_waitcnt lgkmcnt(8)
	v_mfma_f32_32x32x16_bf16 v[66:81], v[192:195], v[112:115], v[66:81]
	s_waitcnt lgkmcnt(7)
	v_mfma_f32_32x32x16_bf16 v[50:65], v[200:203], v[224:227], v[50:65]
	s_waitcnt lgkmcnt(6)
	v_mfma_f32_32x32x16_bf16 v[34:49], v[204:207], v[224:227], v[34:49]
	s_waitcnt lgkmcnt(5)
	v_mfma_f32_32x32x16_bf16 v[18:33], v[208:211], v[224:227], v[18:33]
	s_waitcnt lgkmcnt(4)
	v_mfma_f32_32x32x16_bf16 v[2:17], v[212:215], v[224:227], v[2:17]
	s_waitcnt lgkmcnt(3)
	v_mfma_f32_32x32x16_bf16 v[50:65], v[160:163], v[228:231], v[50:65]
	s_waitcnt lgkmcnt(2)
	v_mfma_f32_32x32x16_bf16 v[34:49], v[164:167], v[228:231], v[34:49]
	s_waitcnt lgkmcnt(1)
	v_mfma_f32_32x32x16_bf16 v[18:33], v[168:171], v[228:231], v[18:33]
	s_waitcnt lgkmcnt(0)
	v_mfma_f32_32x32x16_bf16 v[2:17], v[196:199], v[228:231], v[2:17]
	s_add_i32 s14, s12, 0x42
	s_cmp_ge_i32 s14, s6
	s_cbranch_scc1 .Lpipe_nostage_l
; DI void attn_item(const Params& p, unsigned char* lds, int b, int hd, int qb, float lam) {
;     ...
;     for (int tt = 1; tt < T; ++tt) {
;         if (tt + 1 < T) A_LOAD_REAL(k0r, v0r);
;         attn_s(lds + bc * A_STAGE, tt, qb, qs, sub, l31, h, qf, O, m, l, pb);
;         attn_pv(lds + bc * A_STAGE + A_KB, l31, h, pb, O);
;         if (tt + 1 < T) A_STORE(k0r, v0r, bn);
;         __syncthreads();
;         bp = bc; bc = bn; bn = (bn == 2) ? 0 : bn + 1;
;     }
	s_mul_i32 s4, s7, 0x8c00
	s_add_i32 s4, s4, 0
	v_add_u32_e32 v184, s4, v140
	v_add_u32_e32 v185, v184, v139
	v_add_u32_e32 v184, v184, v141
	s_waitcnt vmcnt(3)
	ds_write_b128 v185, v[116:119]
	s_waitcnt vmcnt(2)
	ds_write_b128 v184, v[120:123]
	v_add3_u32 v184, s4, v150, v151
	v_add_u32_e32 v185, v184, v152
	v_add_u32_e32 v184, v184, v153
	v_add_u32_e32 v185, 0x4000, v185
	v_add_u32_e32 v184, 0x4000, v184
	s_waitcnt vmcnt(1)
	ds_write2_b64 v185, v[124:125], v[126:127] offset0:128 offset1:130
	s_waitcnt vmcnt(0)
	ds_write2_b64 v184, v[128:129], v[130:131] offset0:128 offset1:130
	s_add_i32 s14, s12, 0x43
	s_cmp_ge_i32 s14, s6
	s_cbranch_scc1 .Lpipe_nostage_l
	v_add_co_u32_e32 v184, vcc, 0x10000, v144
	global_load_dwordx4 v[116:119], v[144:145], off
	s_nop 0
	v_addc_co_u32_e32 v185, vcc, 0, v145, vcc
	global_load_dwordx4 v[120:123], v[184:185], off
	global_load_dwordx4 v[124:127], v[142:143], off
	v_add_co_u32_e32 v184, vcc, 0x80000, v142
	v_lshl_add_u64 v[144:145], v[144:145], 0, s[90:91]
	s_nop 0
	v_addc_co_u32_e32 v185, vcc, 0, v143, vcc
	global_load_dwordx4 v[128:131], v[184:185], off
	v_lshl_add_u64 v[142:143], v[142:143], 0, s[88:89]
.Lpipe_nostage_l:
	s_waitcnt lgkmcnt(0)
	s_barrier
	s_branch .Lpipe_loop
.Lpipe_final:
	s_barrier
	s_waitcnt lgkmcnt(7)
	v_mfma_f32_32x32x16_bf16 v[50:65], v[172:175], v[216:219], v[50:65]
	s_waitcnt lgkmcnt(6)
	v_mfma_f32_32x32x16_bf16 v[34:49], v[176:179], v[216:219], v[34:49]
	s_waitcnt lgkmcnt(5)
	v_mfma_f32_32x32x16_bf16 v[18:33], v[180:183], v[216:219], v[18:33]
	s_waitcnt lgkmcnt(4)
	v_mfma_f32_32x32x16_bf16 v[2:17], v[192:195], v[216:219], v[2:17]
	ds_read_b128 v[160:163], v191 offset:17472
	ds_read_b128 v[164:167], v191 offset:22080
	ds_read_b128 v[168:171], v191 offset:26688
	ds_read_b128 v[196:199], v191 offset:31296
	ds_read_b128 v[172:175], v191 offset:17504
	ds_read_b128 v[176:179], v191 offset:22112
	ds_read_b128 v[180:183], v191 offset:26720
	ds_read_b128 v[192:195], v191 offset:31328
	s_waitcnt lgkmcnt(11)
	v_mfma_f32_32x32x16_bf16 v[50:65], v[200:203], v[220:223], v[50:65]
	s_waitcnt lgkmcnt(10)
	v_mfma_f32_32x32x16_bf16 v[34:49], v[204:207], v[220:223], v[34:49]
	s_waitcnt lgkmcnt(9)
	v_mfma_f32_32x32x16_bf16 v[18:33], v[208:211], v[220:223], v[18:33]
	s_waitcnt lgkmcnt(8)
	v_mfma_f32_32x32x16_bf16 v[2:17], v[212:215], v[220:223], v[2:17]
	s_waitcnt lgkmcnt(7)
	v_mfma_f32_32x32x16_bf16 v[50:65], v[160:163], v[224:227], v[50:65]
	s_waitcnt lgkmcnt(6)
	v_mfma_f32_32x32x16_bf16 v[34:49], v[164:167], v[224:227], v[34:49]
	s_waitcnt lgkmcnt(5)
	v_mfma_f32_32x32x16_bf16 v[18:33], v[168:171], v[224:227], v[18:33]
	s_waitcnt lgkmcnt(4)
	v_mfma_f32_32x32x16_bf16 v[2:17], v[196:199], v[224:227], v[2:17]
	s_waitcnt lgkmcnt(3)
	v_mfma_f32_32x32x16_bf16 v[50:65], v[172:175], v[228:231], v[50:65]
	s_waitcnt lgkmcnt(2)
	v_mfma_f32_32x32x16_bf16 v[34:49], v[176:179], v[228:231], v[34:49]
	s_waitcnt lgkmcnt(1)
	v_mfma_f32_32x32x16_bf16 v[18:33], v[180:183], v[228:231], v[18:33]
	s_waitcnt lgkmcnt(0)
	v_mfma_f32_32x32x16_bf16 v[2:17], v[192:195], v[228:231], v[2:17]
	s_barrier
	s_cmp_eq_u32 s99, 1
	s_cbranch_scc1 .Lpipe_done
	s_barrier
.Lpipe_done:
	s_branch .LBB0_1824

; #define LAS __attribute__((address_space(3)))
; #define GRID_BARRIER() { XcdBarrier xb_; xb_.bar = (unsigned*)(p.ws + OFF_XBAR); xb_.x = xb_xcc_id(); xb_.st = (volatile LAS unsigned*)(lds + LDS_ITEM + 16); xcd_barrier(xb_); }
; __global__ void __launch_bounds__(512) hybrid_fwd(Params p) {
;     extern __shared__ __attribute__((aligned(16))) unsigned char lds[];
;     ...
;     run_phase(p, lds, p.phase_lo);
;     ...
;     cg::grid_group grid = cg::this_grid();
;     if (p.phase_lo == 77) grid.sync();
;     {
;         volatile LAS unsigned* st = (volatile LAS unsigned*)(lds + LDS_ITEM + 16);
;         if (threadIdx.x == 0) { st[0] = 0u; st[1] = 0u; }
;         __syncthreads();
;         (void)xcd_barrier_post((unsigned*)(p.ws + OFF_XBAR), st);
;     }
;     ...
;     phase0(p, lds); GRID_BARRIER();
;     phase1(p, lds); GRID_BARRIER();
;     phase15(p, lds); GRID_BARRIER();
;     phase2(p, lds); GRID_BARRIER();
;     phase3(p, lds); GRID_BARRIER();
;     phase4(p, lds);
;     ...
; }
	.amdhsa_kernel _Z10hybrid_fwd6Params
		.amdhsa_group_segment_fixed_size 0
		.amdhsa_private_segment_fixed_size 0
		.amdhsa_kernarg_size 408
		.amdhsa_user_sgpr_count 2
		.amdhsa_user_sgpr_dispatch_ptr 0
		.amdhsa_user_sgpr_queue_ptr 0
		.amdhsa_user_sgpr_kernarg_segment_ptr 1
		.amdhsa_user_sgpr_dispatch_id 0
		.amdhsa_user_sgpr_kernarg_preload_length 0
		.amdhsa_user_sgpr_kernarg_preload_offset 0
		.amdhsa_user_sgpr_private_segment_size 0
		.amdhsa_uses_dynamic_stack 0
		.amdhsa_enable_private_segment 0
		.amdhsa_system_sgpr_workgroup_id_x 1
		.amdhsa_system_sgpr_workgroup_id_y 0
		.amdhsa_system_sgpr_workgroup_id_z 0
		.amdhsa_system_sgpr_workgroup_info 0
		.amdhsa_system_vgpr_workitem_id 2
		.amdhsa_next_free_vgpr 237
		.amdhsa_next_free_sgpr 100
		.amdhsa_accum_offset 240
		.amdhsa_reserve_vcc 1
		.amdhsa_float_round_mode_32 0
		.amdhsa_float_round_mode_16_64 0
		.amdhsa_float_denorm_mode_32 3
		.amdhsa_float_denorm_mode_16_64 3
		.amdhsa_dx10_clamp 1
		.amdhsa_ieee_mode 1
		.amdhsa_fp16_overflow 0
		.amdhsa_tg_split 0
		.amdhsa_exception_fp_ieee_invalid_op 0
		.amdhsa_exception_fp_denorm_src 0
		.amdhsa_exception_fp_ieee_div_zero 0
		.amdhsa_exception_fp_ieee_overflow 0
		.amdhsa_exception_fp_ieee_underflow 0
		.amdhsa_exception_fp_ieee_inexact 0
		.amdhsa_exception_int_div_zero 0
	.end_amdhsa_kernel

; #define LAS __attribute__((address_space(3)))
; #define GRID_BARRIER() { XcdBarrier xb_; xb_.bar = (unsigned*)(p.ws + OFF_XBAR); xb_.x = xb_xcc_id(); xb_.st = (volatile LAS unsigned*)(lds + LDS_ITEM + 16); xcd_barrier(xb_); }
; __global__ void __launch_bounds__(512) hybrid_fwd(Params p) {
;     extern __shared__ __attribute__((aligned(16))) unsigned char lds[];
;     ...
;     run_phase(p, lds, p.phase_lo);
;     ...
;     cg::grid_group grid = cg::this_grid();
;     if (p.phase_lo == 77) grid.sync();
;     {
;         volatile LAS unsigned* st = (volatile LAS unsigned*)(lds + LDS_ITEM + 16);
;         if (threadIdx.x == 0) { st[0] = 0u; st[1] = 0u; }
;         __syncthreads();
;         (void)xcd_barrier_post((unsigned*)(p.ws + OFF_XBAR), st);
;     }
;     ...
;     phase0(p, lds); GRID_BARRIER();
;     phase1(p, lds); GRID_BARRIER();
;     phase15(p, lds); GRID_BARRIER();
;     phase2(p, lds); GRID_BARRIER();
;     phase3(p, lds); GRID_BARRIER();
;     phase4(p, lds);
;     ...
; }
amdhsa.kernels:
  - .agpr_count:     0
    .args:
      - .offset:         0
        .size:           152
        .value_kind:     by_value
      - .offset:         152
        .size:           4
        .value_kind:     hidden_block_count_x
      - .offset:         156
        .size:           4
        .value_kind:     hidden_block_count_y
      - .offset:         160
        .size:           4
        .value_kind:     hidden_block_count_z
      - .offset:         164
        .size:           2
        .value_kind:     hidden_group_size_x
      - .offset:         166
        .size:           2
        .value_kind:     hidden_group_size_y
      - .offset:         168
        .size:           2
        .value_kind:     hidden_group_size_z
      - .offset:         170
        .size:           2
        .value_kind:     hidden_remainder_x
      - .offset:         172
        .size:           2
        .value_kind:     hidden_remainder_y
      - .offset:         174
        .size:           2
        .value_kind:     hidden_remainder_z
      - .offset:         192
        .size:           8
        .value_kind:     hidden_global_offset_x
      - .offset:         200
        .size:           8
        .value_kind:     hidden_global_offset_y
      - .offset:         208
        .size:           8
        .value_kind:     hidden_global_offset_z
      - .offset:         216
        .size:           2
        .value_kind:     hidden_grid_dims
      - .offset:         240
        .size:           8
        .value_kind:     hidden_multigrid_sync_arg
      - .offset:         272
        .size:           4
        .value_kind:     hidden_dynamic_lds_size
    .group_segment_fixed_size: 0
    .kernarg_segment_align: 8
    .kernarg_segment_size: 408
    .language:       OpenCL C
    .language_version:
      - 2
      - 0
    .max_flat_workgroup_size: 512
    .name:           _Z10hybrid_fwd6Params
    .private_segment_fixed_size: 0
    .sgpr_count:     106
    .sgpr_spill_count: 39
    .symbol:         _Z10hybrid_fwd6Params.kd
    .uniform_work_group_size: 1
    .uses_dynamic_stack: false
    .vgpr_count:     237
    .vgpr_spill_count: 0
    .wavefront_size: 64
